# v28 plus early L2 writebacks at the last grid barrier issued by the arrivers with 32/16/8/4/2 workgroups still to come (moves the flush off the barrier critical path)
# speedup vs baseline: 1.0084x; 1.0045x over previous
.LBB0_1025:
	s_or_b64 exec, exec, s[8:9]
	v_cvt_f32_u32_e32 v4, v2
	s_waitcnt vmcnt(0)
	v_readfirstlane_b32 s6, v3
	v_sub_u32_e32 v3, 0, v2
	v_rcp_iflag_f32_e32 v4, v4
	v_add_u32_e32 v5, s6, v1
	v_mul_f32_e32 v4, 0x4f7ffffe, v4
	v_cvt_u32_f32_e32 v4, v4
	v_mul_lo_u32 v1, v3, v4
	v_mul_hi_u32 v1, v4, v1
	v_add_u32_e32 v1, v4, v1
	v_mul_hi_u32 v1, v5, v1
	v_mul_lo_u32 v3, v1, v2
	v_sub_u32_e32 v3, v5, v3
	v_add_u32_e32 v4, 1, v1
	v_cmp_ge_u32_e32 vcc, v3, v2
	s_nop 1
	v_cndmask_b32_e32 v1, v1, v4, vcc
	v_sub_u32_e32 v4, v3, v2
	v_cndmask_b32_e32 v3, v3, v4, vcc
	v_add_u32_e32 v4, 1, v1
	v_cmp_ge_u32_e32 vcc, v3, v2
	v_add_u32_e32 v3, 1, v5
	s_nop 0
	v_cndmask_b32_e32 v1, v1, v4, vcc
	v_mul_lo_u32 v4, v2, v1
	v_add_u32_e32 v2, v4, v2
	v_cmp_ne_u32_e32 vcc, v3, v2
	s_and_saveexec_b64 s[6:7], vcc
	s_xor_b64 s[6:7], exec, s[6:7]
	s_cbranch_execz .LBB0_1039
	v_sub_u32_e32 v3, v2, v5
	v_add_u32_e32 v4, -1, v3
	v_and_b32_e32 v3, v3, v4
	v_cmp_eq_u32_e32 vcc, 0, v3
	s_cbranch_vccz .Lg4_noflush
	buffer_wbl2 sc1
